# P8 fused epilogue: X1B load of each ladder step issued one step early (two in flight), s_nop 1 behind the stores for the store-data hazard; on v97
# speedup vs baseline: 1.0079x; 1.0079x over previous
.LBB0_1042:
	s_or_b64 exec, exec, s[4:5]
	v_add_u32_e32 v148, s3, v1
	v_ashrrev_i32_e32 v149, 31, v148
	s_waitcnt lgkmcnt(0)
	v_lshlrev_b64 v[150:151], 11, v[148:149]
	v_lshl_add_u64 v[154:155], v[150:151], 0, v[146:147]
	s_waitcnt lgkmcnt(0)
	s_barrier
	v_lshl_add_u64 v[156:157], v[154:155], 1, s[52:53]
	global_load_dwordx4 v[236:239], v[156:157], off nt
	v_lshl_add_u32 v1, v1, 2, 0
	ds_read_b32 v158, v1 offset:8192
	v_lshl_add_u64 v[154:155], v[154:155], 2, s[24:25]
	s_waitcnt lgkmcnt(0)
	v_pk_mul_f32 v[126:127], v[126:127], v[158:159] op_sel_hi:[1,0]
	v_pk_mul_f32 v[128:129], v[128:129], v[158:159] op_sel_hi:[1,0]
	v_pk_mul_f32 v[160:161], v[122:123], v[158:159] op_sel_hi:[1,0]
	v_pk_mul_f32 v[162:163], v[124:125], v[158:159] op_sel_hi:[1,0]
	v_pk_mul_f32 v[118:119], v[118:119], v[158:159] op_sel_hi:[1,0]
	v_pk_mul_f32 v[120:121], v[120:121], v[158:159] op_sel_hi:[1,0]
	global_load_dwordx4 v[240:243], v[156:157], off offset:256 nt
	s_waitcnt vmcnt(1)
	v_mov_b32_e32 v150, v236
	v_mov_b32_e32 v151, v237
	v_mov_b32_e32 v152, v238
	v_mov_b32_e32 v153, v239
	v_lshlrev_b32_e32 v122, 16, v150
	v_and_b32_e32 v123, 0xffff0000, v150
	v_lshlrev_b32_e32 v124, 16, v151
	v_and_b32_e32 v125, 0xffff0000, v151
	v_lshlrev_b32_e32 v150, 16, v152
	v_and_b32_e32 v151, 0xffff0000, v152
	v_lshlrev_b32_e32 v152, 16, v153
	v_and_b32_e32 v153, 0xffff0000, v153
	v_pk_fma_f32 v[124:125], v[144:145], v[128:129], v[124:125]
	v_pk_fma_f32 v[122:123], v[142:143], v[126:127], v[122:123]
	v_pk_fma_f32 v[128:129], v[140:141], v[162:163], v[152:153]
	v_pk_fma_f32 v[126:127], v[138:139], v[160:161], v[150:151]
	global_store_dwordx4 v[154:155], v[122:125], off nt
	global_store_dwordx4 v[154:155], v[126:129], off offset:16 nt
	s_nop 1
	v_pk_mul_f32 v[150:151], v[114:115], v[158:159] op_sel_hi:[1,0]
	v_add_u32_e32 v126, 16, v148
	v_ashrrev_i32_e32 v127, 31, v126
	v_pk_mul_f32 v[152:153], v[116:117], v[158:159] op_sel_hi:[1,0]
	v_lshlrev_b64 v[126:127], 11, v[126:127]
	v_lshl_add_u64 v[126:127], v[126:127], 0, v[146:147]
	v_lshl_add_u64 v[128:129], v[126:127], 1, s[52:53]
	global_load_dwordx4 v[236:239], v[128:129], off nt
	s_waitcnt vmcnt(1)
	v_mov_b32_e32 v122, v240
	v_mov_b32_e32 v123, v241
	v_mov_b32_e32 v124, v242
	v_mov_b32_e32 v125, v243
	v_lshlrev_b32_e32 v114, 16, v122
	v_and_b32_e32 v115, 0xffff0000, v122
	v_lshlrev_b32_e32 v116, 16, v123
	v_and_b32_e32 v117, 0xffff0000, v123
	v_lshlrev_b32_e32 v122, 16, v124
	v_and_b32_e32 v123, 0xffff0000, v124
	v_lshlrev_b32_e32 v124, 16, v125
	v_and_b32_e32 v125, 0xffff0000, v125
	v_pk_fma_f32 v[116:117], v[136:137], v[120:121], v[116:117]
	v_pk_fma_f32 v[114:115], v[134:135], v[118:119], v[114:115]
	v_pk_fma_f32 v[120:121], v[132:133], v[152:153], v[124:125]
	v_pk_fma_f32 v[118:119], v[130:131], v[150:151], v[122:123]
	global_store_dwordx4 v[154:155], v[114:117], off offset:512 nt
	global_store_dwordx4 v[154:155], v[118:121], off offset:528 nt
	s_nop 1
	ds_read_b32 v118, v1 offset:8256
	v_lshl_add_u64 v[120:121], v[126:127], 2, s[24:25]
	s_waitcnt lgkmcnt(0)
	v_pk_mul_f32 v[110:111], v[110:111], v[118:119] op_sel_hi:[1,0]
	v_pk_mul_f32 v[112:113], v[112:113], v[118:119] op_sel_hi:[1,0]
	v_pk_mul_f32 v[122:123], v[106:107], v[118:119] op_sel_hi:[1,0]
	v_pk_mul_f32 v[124:125], v[108:109], v[118:119] op_sel_hi:[1,0]
	v_pk_mul_f32 v[102:103], v[102:103], v[118:119] op_sel_hi:[1,0]
	v_pk_mul_f32 v[104:105], v[104:105], v[118:119] op_sel_hi:[1,0]
	global_load_dwordx4 v[240:243], v[128:129], off offset:256 nt
	s_waitcnt vmcnt(1)
	v_mov_b32_e32 v114, v236
	v_mov_b32_e32 v115, v237
	v_mov_b32_e32 v116, v238
	v_mov_b32_e32 v117, v239
	v_lshlrev_b32_e32 v106, 16, v114
	v_and_b32_e32 v107, 0xffff0000, v114
	v_lshlrev_b32_e32 v108, 16, v115
	v_and_b32_e32 v109, 0xffff0000, v115
	v_lshlrev_b32_e32 v114, 16, v116
	v_and_b32_e32 v115, 0xffff0000, v116
	v_lshlrev_b32_e32 v116, 16, v117
	v_and_b32_e32 v117, 0xffff0000, v117
	v_pk_fma_f32 v[108:109], v[144:145], v[112:113], v[108:109]
	v_pk_fma_f32 v[106:107], v[142:143], v[110:111], v[106:107]
	v_pk_fma_f32 v[112:113], v[140:141], v[124:125], v[116:117]
	v_pk_fma_f32 v[110:111], v[138:139], v[122:123], v[114:115]
	global_store_dwordx4 v[120:121], v[106:109], off nt
	global_store_dwordx4 v[120:121], v[110:113], off offset:16 nt
	s_nop 1
	v_pk_mul_f32 v[114:115], v[98:99], v[118:119] op_sel_hi:[1,0]
	v_add_u32_e32 v110, 32, v148
	v_ashrrev_i32_e32 v111, 31, v110
	v_pk_mul_f32 v[116:117], v[100:101], v[118:119] op_sel_hi:[1,0]
	v_lshlrev_b64 v[110:111], 11, v[110:111]
	v_lshl_add_u64 v[110:111], v[110:111], 0, v[146:147]
	v_lshl_add_u64 v[112:113], v[110:111], 1, s[52:53]
	global_load_dwordx4 v[236:239], v[112:113], off nt
	s_waitcnt vmcnt(1)
	v_mov_b32_e32 v106, v240
	v_mov_b32_e32 v107, v241
	v_mov_b32_e32 v108, v242
	v_mov_b32_e32 v109, v243
	v_lshlrev_b32_e32 v98, 16, v106
	v_and_b32_e32 v99, 0xffff0000, v106
	v_lshlrev_b32_e32 v100, 16, v107
	v_and_b32_e32 v101, 0xffff0000, v107
	v_lshlrev_b32_e32 v106, 16, v108
	v_and_b32_e32 v107, 0xffff0000, v108
	v_lshlrev_b32_e32 v108, 16, v109
	v_and_b32_e32 v109, 0xffff0000, v109
	v_pk_fma_f32 v[100:101], v[136:137], v[104:105], v[100:101]
	v_pk_fma_f32 v[98:99], v[134:135], v[102:103], v[98:99]
	v_pk_fma_f32 v[104:105], v[132:133], v[116:117], v[108:109]
	v_pk_fma_f32 v[102:103], v[130:131], v[114:115], v[106:107]
	global_store_dwordx4 v[120:121], v[98:101], off offset:512 nt
	global_store_dwordx4 v[120:121], v[102:105], off offset:528 nt
	s_nop 1
	ds_read_b32 v102, v1 offset:8320
	v_lshl_add_u64 v[104:105], v[110:111], 2, s[24:25]
	s_waitcnt lgkmcnt(0)
	v_pk_mul_f32 v[94:95], v[94:95], v[102:103] op_sel_hi:[1,0]
	v_pk_mul_f32 v[96:97], v[96:97], v[102:103] op_sel_hi:[1,0]
	v_pk_mul_f32 v[106:107], v[90:91], v[102:103] op_sel_hi:[1,0]
	v_pk_mul_f32 v[108:109], v[92:93], v[102:103] op_sel_hi:[1,0]
	v_pk_mul_f32 v[86:87], v[86:87], v[102:103] op_sel_hi:[1,0]
	v_pk_mul_f32 v[88:89], v[88:89], v[102:103] op_sel_hi:[1,0]
	global_load_dwordx4 v[240:243], v[112:113], off offset:256 nt
	s_waitcnt vmcnt(1)
	v_mov_b32_e32 v98, v236
	v_mov_b32_e32 v99, v237
	v_mov_b32_e32 v100, v238
	v_mov_b32_e32 v101, v239
	v_lshlrev_b32_e32 v90, 16, v98
	v_and_b32_e32 v91, 0xffff0000, v98
	v_lshlrev_b32_e32 v92, 16, v99
	v_and_b32_e32 v93, 0xffff0000, v99
	v_lshlrev_b32_e32 v98, 16, v100
	v_and_b32_e32 v99, 0xffff0000, v100
	v_lshlrev_b32_e32 v100, 16, v101
	v_and_b32_e32 v101, 0xffff0000, v101
	v_pk_fma_f32 v[92:93], v[144:145], v[96:97], v[92:93]
	v_pk_fma_f32 v[90:91], v[142:143], v[94:95], v[90:91]
	v_pk_fma_f32 v[96:97], v[140:141], v[108:109], v[100:101]
	v_pk_fma_f32 v[94:95], v[138:139], v[106:107], v[98:99]
	global_store_dwordx4 v[104:105], v[90:93], off nt
	global_store_dwordx4 v[104:105], v[94:97], off offset:16 nt
	s_nop 1
	v_pk_mul_f32 v[98:99], v[82:83], v[102:103] op_sel_hi:[1,0]
	v_add_u32_e32 v94, 48, v148
	v_ashrrev_i32_e32 v95, 31, v94
	v_pk_mul_f32 v[100:101], v[84:85], v[102:103] op_sel_hi:[1,0]
	v_lshlrev_b64 v[94:95], 11, v[94:95]
	v_lshl_add_u64 v[94:95], v[94:95], 0, v[146:147]
	v_lshl_add_u64 v[96:97], v[94:95], 1, s[52:53]
	global_load_dwordx4 v[236:239], v[96:97], off nt
	s_waitcnt vmcnt(1)
	v_mov_b32_e32 v90, v240
	v_mov_b32_e32 v91, v241
	v_mov_b32_e32 v92, v242
	v_mov_b32_e32 v93, v243
	v_lshlrev_b32_e32 v82, 16, v90
	v_and_b32_e32 v83, 0xffff0000, v90
	v_lshlrev_b32_e32 v84, 16, v91
	v_and_b32_e32 v85, 0xffff0000, v91
	v_lshlrev_b32_e32 v90, 16, v92
	v_and_b32_e32 v91, 0xffff0000, v92
	v_lshlrev_b32_e32 v92, 16, v93
	v_and_b32_e32 v93, 0xffff0000, v93
	v_pk_fma_f32 v[84:85], v[136:137], v[88:89], v[84:85]
	v_pk_fma_f32 v[82:83], v[134:135], v[86:87], v[82:83]
	v_pk_fma_f32 v[88:89], v[132:133], v[100:101], v[92:93]
	v_pk_fma_f32 v[86:87], v[130:131], v[98:99], v[90:91]
	global_store_dwordx4 v[104:105], v[82:85], off offset:512 nt
	global_store_dwordx4 v[104:105], v[86:89], off offset:528 nt
	s_nop 1
	ds_read_b32 v86, v1 offset:8384
	v_lshl_add_u64 v[88:89], v[94:95], 2, s[24:25]
	s_waitcnt lgkmcnt(0)
	v_pk_mul_f32 v[78:79], v[78:79], v[86:87] op_sel_hi:[1,0]
	v_pk_mul_f32 v[80:81], v[80:81], v[86:87] op_sel_hi:[1,0]
	v_pk_mul_f32 v[90:91], v[74:75], v[86:87] op_sel_hi:[1,0]
	v_pk_mul_f32 v[92:93], v[76:77], v[86:87] op_sel_hi:[1,0]
	v_pk_mul_f32 v[70:71], v[70:71], v[86:87] op_sel_hi:[1,0]
	v_pk_mul_f32 v[72:73], v[72:73], v[86:87] op_sel_hi:[1,0]
	global_load_dwordx4 v[240:243], v[96:97], off offset:256 nt
	s_waitcnt vmcnt(1)
	v_mov_b32_e32 v82, v236
	v_mov_b32_e32 v83, v237
	v_mov_b32_e32 v84, v238
	v_mov_b32_e32 v85, v239
	v_lshlrev_b32_e32 v74, 16, v82
	v_and_b32_e32 v75, 0xffff0000, v82
	v_lshlrev_b32_e32 v76, 16, v83
	v_and_b32_e32 v77, 0xffff0000, v83
	v_lshlrev_b32_e32 v82, 16, v84
	v_and_b32_e32 v83, 0xffff0000, v84
	v_lshlrev_b32_e32 v84, 16, v85
	v_and_b32_e32 v85, 0xffff0000, v85
	v_pk_fma_f32 v[76:77], v[144:145], v[80:81], v[76:77]
	v_pk_fma_f32 v[74:75], v[142:143], v[78:79], v[74:75]
	v_pk_fma_f32 v[80:81], v[140:141], v[92:93], v[84:85]
	v_pk_fma_f32 v[78:79], v[138:139], v[90:91], v[82:83]
	global_store_dwordx4 v[88:89], v[74:77], off nt
	global_store_dwordx4 v[88:89], v[78:81], off offset:16 nt
	s_nop 1
	v_pk_mul_f32 v[82:83], v[66:67], v[86:87] op_sel_hi:[1,0]
	v_add_u32_e32 v78, 0x80, v148
	v_ashrrev_i32_e32 v79, 31, v78
	v_pk_mul_f32 v[84:85], v[68:69], v[86:87] op_sel_hi:[1,0]
	v_lshlrev_b64 v[78:79], 11, v[78:79]
	v_lshl_add_u64 v[78:79], v[78:79], 0, v[146:147]
	v_lshl_add_u64 v[80:81], v[78:79], 1, s[52:53]
	global_load_dwordx4 v[236:239], v[80:81], off nt
	s_waitcnt vmcnt(1)
	v_mov_b32_e32 v74, v240
	v_mov_b32_e32 v75, v241
	v_mov_b32_e32 v76, v242
	v_mov_b32_e32 v77, v243
	v_lshlrev_b32_e32 v66, 16, v74
	v_and_b32_e32 v67, 0xffff0000, v74
	v_lshlrev_b32_e32 v68, 16, v75
	v_and_b32_e32 v69, 0xffff0000, v75
	v_lshlrev_b32_e32 v74, 16, v76
	v_and_b32_e32 v75, 0xffff0000, v76
	v_lshlrev_b32_e32 v76, 16, v77
	v_and_b32_e32 v77, 0xffff0000, v77
	v_pk_fma_f32 v[68:69], v[136:137], v[72:73], v[68:69]
	v_pk_fma_f32 v[66:67], v[134:135], v[70:71], v[66:67]
	v_pk_fma_f32 v[72:73], v[132:133], v[84:85], v[76:77]
	v_pk_fma_f32 v[70:71], v[130:131], v[82:83], v[74:75]
	global_store_dwordx4 v[88:89], v[66:69], off offset:512 nt
	global_store_dwordx4 v[88:89], v[70:73], off offset:528 nt
	s_nop 1
	ds_read_b32 v70, v1 offset:8704
	v_lshl_add_u64 v[72:73], v[78:79], 2, s[24:25]
	s_waitcnt lgkmcnt(0)
	v_pk_mul_f32 v[62:63], v[62:63], v[70:71] op_sel_hi:[1,0]
	v_pk_mul_f32 v[64:65], v[64:65], v[70:71] op_sel_hi:[1,0]
	v_pk_mul_f32 v[74:75], v[58:59], v[70:71] op_sel_hi:[1,0]
	v_pk_mul_f32 v[76:77], v[60:61], v[70:71] op_sel_hi:[1,0]
	v_pk_mul_f32 v[54:55], v[54:55], v[70:71] op_sel_hi:[1,0]
	v_pk_mul_f32 v[56:57], v[56:57], v[70:71] op_sel_hi:[1,0]
	global_load_dwordx4 v[240:243], v[80:81], off offset:256 nt
	s_waitcnt vmcnt(1)
	v_mov_b32_e32 v66, v236
	v_mov_b32_e32 v67, v237
	v_mov_b32_e32 v68, v238
	v_mov_b32_e32 v69, v239
	v_lshlrev_b32_e32 v58, 16, v66
	v_and_b32_e32 v59, 0xffff0000, v66
	v_lshlrev_b32_e32 v60, 16, v67
	v_and_b32_e32 v61, 0xffff0000, v67
	v_lshlrev_b32_e32 v66, 16, v68
	v_and_b32_e32 v67, 0xffff0000, v68
	v_lshlrev_b32_e32 v68, 16, v69
	v_and_b32_e32 v69, 0xffff0000, v69
	v_pk_fma_f32 v[60:61], v[144:145], v[64:65], v[60:61]
	v_pk_fma_f32 v[58:59], v[142:143], v[62:63], v[58:59]
	v_pk_fma_f32 v[64:65], v[140:141], v[76:77], v[68:69]
	v_pk_fma_f32 v[62:63], v[138:139], v[74:75], v[66:67]
	global_store_dwordx4 v[72:73], v[58:61], off nt
	global_store_dwordx4 v[72:73], v[62:65], off offset:16 nt
	s_nop 1
	v_pk_mul_f32 v[66:67], v[50:51], v[70:71] op_sel_hi:[1,0]
	v_add_u32_e32 v62, 0x90, v148
	v_ashrrev_i32_e32 v63, 31, v62
	v_pk_mul_f32 v[68:69], v[52:53], v[70:71] op_sel_hi:[1,0]
	v_lshlrev_b64 v[62:63], 11, v[62:63]
	v_lshl_add_u64 v[62:63], v[62:63], 0, v[146:147]
	v_lshl_add_u64 v[64:65], v[62:63], 1, s[52:53]
	global_load_dwordx4 v[236:239], v[64:65], off nt
	s_waitcnt vmcnt(1)
	v_mov_b32_e32 v58, v240
	v_mov_b32_e32 v59, v241
	v_mov_b32_e32 v60, v242
	v_mov_b32_e32 v61, v243
	v_lshlrev_b32_e32 v50, 16, v58
	v_and_b32_e32 v51, 0xffff0000, v58
	v_lshlrev_b32_e32 v52, 16, v59
	v_and_b32_e32 v53, 0xffff0000, v59
	v_lshlrev_b32_e32 v58, 16, v60
	v_and_b32_e32 v59, 0xffff0000, v60
	v_lshlrev_b32_e32 v60, 16, v61
	v_and_b32_e32 v61, 0xffff0000, v61
	v_pk_fma_f32 v[52:53], v[136:137], v[56:57], v[52:53]
	v_pk_fma_f32 v[50:51], v[134:135], v[54:55], v[50:51]
	v_pk_fma_f32 v[56:57], v[132:133], v[68:69], v[60:61]
	v_pk_fma_f32 v[54:55], v[130:131], v[66:67], v[58:59]
	global_store_dwordx4 v[72:73], v[50:53], off offset:512 nt
	global_store_dwordx4 v[72:73], v[54:57], off offset:528 nt
	s_nop 1
	ds_read_b32 v54, v1 offset:8768
	v_lshl_add_u64 v[56:57], v[62:63], 2, s[24:25]
	s_waitcnt lgkmcnt(0)
	v_pk_mul_f32 v[46:47], v[46:47], v[54:55] op_sel_hi:[1,0]
	v_pk_mul_f32 v[48:49], v[48:49], v[54:55] op_sel_hi:[1,0]
	v_pk_mul_f32 v[58:59], v[42:43], v[54:55] op_sel_hi:[1,0]
	v_pk_mul_f32 v[60:61], v[44:45], v[54:55] op_sel_hi:[1,0]
	v_pk_mul_f32 v[38:39], v[38:39], v[54:55] op_sel_hi:[1,0]
	v_pk_mul_f32 v[40:41], v[40:41], v[54:55] op_sel_hi:[1,0]
	global_load_dwordx4 v[240:243], v[64:65], off offset:256 nt
	s_waitcnt vmcnt(1)
	v_mov_b32_e32 v50, v236
	v_mov_b32_e32 v51, v237
	v_mov_b32_e32 v52, v238
	v_mov_b32_e32 v53, v239
	v_lshlrev_b32_e32 v42, 16, v50
	v_and_b32_e32 v43, 0xffff0000, v50
	v_lshlrev_b32_e32 v44, 16, v51
	v_and_b32_e32 v45, 0xffff0000, v51
	v_lshlrev_b32_e32 v50, 16, v52
	v_and_b32_e32 v51, 0xffff0000, v52
	v_lshlrev_b32_e32 v52, 16, v53
	v_and_b32_e32 v53, 0xffff0000, v53
	v_pk_fma_f32 v[44:45], v[144:145], v[48:49], v[44:45]
	v_pk_fma_f32 v[42:43], v[142:143], v[46:47], v[42:43]
	v_pk_fma_f32 v[48:49], v[140:141], v[60:61], v[52:53]
	v_pk_fma_f32 v[46:47], v[138:139], v[58:59], v[50:51]
	global_store_dwordx4 v[56:57], v[42:45], off nt
	global_store_dwordx4 v[56:57], v[46:49], off offset:16 nt
	s_nop 1
	v_pk_mul_f32 v[50:51], v[34:35], v[54:55] op_sel_hi:[1,0]
	v_add_u32_e32 v46, 0xa0, v148
	v_ashrrev_i32_e32 v47, 31, v46
	v_pk_mul_f32 v[52:53], v[36:37], v[54:55] op_sel_hi:[1,0]
	v_lshlrev_b64 v[46:47], 11, v[46:47]
	v_lshl_add_u64 v[46:47], v[46:47], 0, v[146:147]
	v_lshl_add_u64 v[48:49], v[46:47], 1, s[52:53]
	global_load_dwordx4 v[236:239], v[48:49], off nt
	s_waitcnt vmcnt(1)
	v_mov_b32_e32 v42, v240
	v_mov_b32_e32 v43, v241
	v_mov_b32_e32 v44, v242
	v_mov_b32_e32 v45, v243
	v_lshlrev_b32_e32 v34, 16, v42
	v_and_b32_e32 v35, 0xffff0000, v42
	v_lshlrev_b32_e32 v36, 16, v43
	v_and_b32_e32 v37, 0xffff0000, v43
	v_lshlrev_b32_e32 v42, 16, v44
	v_and_b32_e32 v43, 0xffff0000, v44
	v_lshlrev_b32_e32 v44, 16, v45
	v_and_b32_e32 v45, 0xffff0000, v45
	v_pk_fma_f32 v[36:37], v[136:137], v[40:41], v[36:37]
	v_pk_fma_f32 v[34:35], v[134:135], v[38:39], v[34:35]
	v_pk_fma_f32 v[40:41], v[132:133], v[52:53], v[44:45]
	v_pk_fma_f32 v[38:39], v[130:131], v[50:51], v[42:43]
	global_store_dwordx4 v[56:57], v[34:37], off offset:512 nt
	global_store_dwordx4 v[56:57], v[38:41], off offset:528 nt
	s_nop 1
	ds_read_b32 v38, v1 offset:8832
	v_lshl_add_u64 v[40:41], v[46:47], 2, s[24:25]
	s_waitcnt lgkmcnt(0)
	v_pk_mul_f32 v[30:31], v[30:31], v[38:39] op_sel_hi:[1,0]
	v_pk_mul_f32 v[32:33], v[32:33], v[38:39] op_sel_hi:[1,0]
	v_pk_mul_f32 v[42:43], v[26:27], v[38:39] op_sel_hi:[1,0]
	v_pk_mul_f32 v[44:45], v[28:29], v[38:39] op_sel_hi:[1,0]
	v_pk_mul_f32 v[22:23], v[22:23], v[38:39] op_sel_hi:[1,0]
	v_pk_mul_f32 v[24:25], v[24:25], v[38:39] op_sel_hi:[1,0]
	global_load_dwordx4 v[240:243], v[48:49], off offset:256 nt
	s_waitcnt vmcnt(1)
	v_mov_b32_e32 v34, v236
	v_mov_b32_e32 v35, v237
	v_mov_b32_e32 v36, v238
	v_mov_b32_e32 v37, v239
	v_lshlrev_b32_e32 v26, 16, v34
	v_and_b32_e32 v27, 0xffff0000, v34
	v_lshlrev_b32_e32 v28, 16, v35
	v_and_b32_e32 v29, 0xffff0000, v35
	v_lshlrev_b32_e32 v34, 16, v36
	v_and_b32_e32 v35, 0xffff0000, v36
	v_lshlrev_b32_e32 v36, 16, v37
	v_and_b32_e32 v37, 0xffff0000, v37
	v_pk_fma_f32 v[28:29], v[144:145], v[32:33], v[28:29]
	v_pk_fma_f32 v[26:27], v[142:143], v[30:31], v[26:27]
	v_pk_fma_f32 v[32:33], v[140:141], v[44:45], v[36:37]
	v_pk_fma_f32 v[30:31], v[138:139], v[42:43], v[34:35]
	global_store_dwordx4 v[40:41], v[26:29], off nt
	global_store_dwordx4 v[40:41], v[30:33], off offset:16 nt
	s_nop 1
	v_pk_mul_f32 v[34:35], v[18:19], v[38:39] op_sel_hi:[1,0]
	v_add_u32_e32 v30, 0xb0, v148
	v_ashrrev_i32_e32 v31, 31, v30
	v_pk_mul_f32 v[36:37], v[20:21], v[38:39] op_sel_hi:[1,0]
	v_lshlrev_b64 v[30:31], 11, v[30:31]
	v_lshl_add_u64 v[30:31], v[30:31], 0, v[146:147]
	v_lshl_add_u64 v[32:33], v[30:31], 1, s[52:53]
	global_load_dwordx4 v[236:239], v[32:33], off nt
	s_waitcnt vmcnt(1)
	v_mov_b32_e32 v26, v240
	v_mov_b32_e32 v27, v241
	v_mov_b32_e32 v28, v242
	v_mov_b32_e32 v29, v243
	v_lshlrev_b32_e32 v18, 16, v26
	v_and_b32_e32 v19, 0xffff0000, v26
	v_lshlrev_b32_e32 v20, 16, v27
	v_and_b32_e32 v21, 0xffff0000, v27
	v_lshlrev_b32_e32 v26, 16, v28
	v_and_b32_e32 v27, 0xffff0000, v28
	v_lshlrev_b32_e32 v28, 16, v29
	v_and_b32_e32 v29, 0xffff0000, v29
	v_pk_fma_f32 v[20:21], v[136:137], v[24:25], v[20:21]
	v_pk_fma_f32 v[18:19], v[134:135], v[22:23], v[18:19]
	v_pk_fma_f32 v[24:25], v[132:133], v[36:37], v[28:29]
	v_pk_fma_f32 v[22:23], v[130:131], v[34:35], v[26:27]
	global_store_dwordx4 v[40:41], v[18:21], off offset:512 nt
	global_store_dwordx4 v[40:41], v[22:25], off offset:528 nt
	s_nop 1
	ds_read_b32 v22, v1 offset:8896
	v_lshl_add_u64 v[24:25], v[30:31], 2, s[24:25]
	s_waitcnt lgkmcnt(0)
	v_pk_mul_f32 v[14:15], v[14:15], v[22:23] op_sel_hi:[1,0]
	v_pk_mul_f32 v[16:17], v[16:17], v[22:23] op_sel_hi:[1,0]
	v_pk_mul_f32 v[26:27], v[10:11], v[22:23] op_sel_hi:[1,0]
	v_pk_mul_f32 v[28:29], v[12:13], v[22:23] op_sel_hi:[1,0]
	v_pk_mul_f32 v[6:7], v[6:7], v[22:23] op_sel_hi:[1,0]
	v_pk_mul_f32 v[8:9], v[8:9], v[22:23] op_sel_hi:[1,0]
	global_load_dwordx4 v[240:243], v[32:33], off offset:256 nt
	s_waitcnt vmcnt(1)
	v_mov_b32_e32 v18, v236
	v_mov_b32_e32 v19, v237
	v_mov_b32_e32 v20, v238
	v_mov_b32_e32 v21, v239
	v_lshlrev_b32_e32 v10, 16, v18
	v_and_b32_e32 v11, 0xffff0000, v18
	v_lshlrev_b32_e32 v12, 16, v19
	v_and_b32_e32 v13, 0xffff0000, v19
	v_lshlrev_b32_e32 v18, 16, v20
	v_and_b32_e32 v19, 0xffff0000, v20
	v_lshlrev_b32_e32 v20, 16, v21
	v_and_b32_e32 v21, 0xffff0000, v21
	v_pk_fma_f32 v[12:13], v[144:145], v[16:17], v[12:13]
	v_pk_fma_f32 v[10:11], v[142:143], v[14:15], v[10:11]
	v_pk_fma_f32 v[16:17], v[140:141], v[28:29], v[20:21]
	v_pk_fma_f32 v[14:15], v[138:139], v[26:27], v[18:19]
	global_store_dwordx4 v[24:25], v[10:13], off nt
	global_store_dwordx4 v[24:25], v[14:17], off offset:16 nt
	s_nop 1
	s_nop 0
	v_pk_mul_f32 v[14:15], v[2:3], v[22:23] op_sel_hi:[1,0]
	v_pk_mul_f32 v[16:17], v[4:5], v[22:23] op_sel_hi:[1,0]
	s_waitcnt vmcnt(0)
	v_mov_b32_e32 v10, v240
	v_mov_b32_e32 v11, v241
	v_mov_b32_e32 v12, v242
	v_mov_b32_e32 v13, v243
	v_lshlrev_b32_e32 v2, 16, v10
	v_and_b32_e32 v3, 0xffff0000, v10
	v_lshlrev_b32_e32 v4, 16, v11
	v_and_b32_e32 v5, 0xffff0000, v11
	v_lshlrev_b32_e32 v10, 16, v12
	v_and_b32_e32 v11, 0xffff0000, v12
	v_lshlrev_b32_e32 v12, 16, v13
	v_and_b32_e32 v13, 0xffff0000, v13
	v_pk_fma_f32 v[4:5], v[136:137], v[8:9], v[4:5]
	v_pk_fma_f32 v[2:3], v[134:135], v[6:7], v[2:3]
	v_pk_fma_f32 v[8:9], v[132:133], v[16:17], v[12:13]
	v_pk_fma_f32 v[6:7], v[130:131], v[14:15], v[10:11]
	global_store_dwordx4 v[24:25], v[2:5], off offset:512 nt
	global_store_dwordx4 v[24:25], v[6:9], off offset:528 nt
	s_nop 1
